# combined: S8 context tiles split in row halves + rope table loads hoisted to tile-loop top + work-queue index claimed one item ahead
# speedup vs baseline: 1.0031x; 1.0031x over previous
; #define LAS __attribute__((address_space(3)))
; DEV bf16x8 pack8(const float* x) { u32x4 o; o.x = pk2(x[0], x[1]); o.y = pk2(x[2], x[3]); o.z = pk2(x[4], x[5]); o.w = pk2(x[6], x[7]); return __builtin_bit_cast(bf16x8, o); }
; DEV void attn_item(const Fr& F, int l, int b, int qb, int kvh, bool ctxq) {
;     ...
;         for (int i = 0; i < 2; ++i) { const int idx = tid + NTHR * i; const int s_ = idx >> 3, c8 = (idx & 7) * 8;
;             float x[8]; unpack8(rk[i], x);
;             if (rope) { float pr[8]; unpack8(rp[i], pr); const bool second = (c8 & 16) != 0; const int n = kb * 128 + s_;
;                 const int pos = (c8 >= 32) ? (n & 63) : (n >> 6); const float* tb = F.ROPE + (size_t)(pos * 16 + (c8 & 8)) * 2;
; #pragma unroll
;                 for (int e = 0; e < 8; ++e) { const float c = tb[2 * e], sn = tb[2 * e + 1]; x[e] = second ? (x[e] * c + pr[e] * sn) : (x[e] * c - pr[e] * sn); } }
;             *(LAS bf16x8*)(Ks + s_ * 72 + c8) = pack8(x);
;             *(LAS u32x4*)(Vs + s_ * 72 + c8) = rv[i]; }
.LBB0_501:
	s_add_i32 s6, s65, s62
	s_cmp_gt_i32 s65, 1
	s_cselect_b64 s[38:39], -1, 0
	s_lshl_b32 s6, s6, 7
	s_addk_i32 s6, 0xfe80
	s_waitcnt vmcnt(5)
	s_cmp_lt_i32 s65, 2
	s_cbranch_scc1 .Lrp_skip
	v_readlane_b32 s40, v242, 28
	v_readlane_b32 s41, v242, 29
	v_add_u32_e32 v1, s6, v141
	v_ashrrev_i32_e32 v1, 6, v1
	v_cndmask_b32_e64 v1, v1, v208, s[50:51]
	v_lshl_or_b32 v82, v1, 4, v206
	v_ashrrev_i32_e32 v83, 31, v82
	v_lshl_add_u64 v[94:95], v[82:83], 3, s[40:41]
	global_load_dwordx4 v[82:85], v[94:95], off offset:48
	global_load_dwordx4 v[86:89], v[94:95], off offset:32
	global_load_dwordx4 v[90:93], v[94:95], off offset:16
	s_nop 0
	global_load_dwordx4 v[94:97], v[94:95], off
	v_add_u32_e32 v1, s6, v151
	v_ashrrev_i32_e32 v1, 6, v1
	v_cndmask_b32_e64 v1, v1, v161, s[50:51]
	v_lshl_or_b32 v102, v1, 4, v206
	v_ashrrev_i32_e32 v103, 31, v102
	v_lshl_add_u64 v[114:115], v[102:103], 3, s[40:41]
	global_load_dwordx4 v[102:105], v[114:115], off offset:48
	global_load_dwordx4 v[106:109], v[114:115], off offset:32
	global_load_dwordx4 v[110:113], v[114:115], off offset:16
	s_nop 0
	global_load_dwordx4 v[114:117], v[114:115], off
.Lrp_skip:
	s_cmp_lt_i32 s65, 2
	v_lshlrev_b32_e32 v2, 16, v28
	v_and_b32_e32 v3, 0xffff0000, v28
	v_lshlrev_b32_e32 v76, 16, v29
	v_and_b32_e32 v77, 0xffff0000, v29
	v_lshlrev_b32_e32 v78, 16, v30
	v_and_b32_e32 v79, 0xffff0000, v30
	v_lshlrev_b32_e32 v80, 16, v31
	v_and_b32_e32 v81, 0xffff0000, v31
	s_barrier
	s_cbranch_scc1 .LBB0_503
	s_waitcnt vmcnt(11)
	v_lshlrev_b32_e32 v98, 16, v44
	v_and_b32_e32 v99, 0xffff0000, v44
	s_waitcnt vmcnt(4)
	v_mov_b32_e32 v101, v96
	v_mov_b32_e32 v96, v95
	v_mov_b32_e32 v100, v94
	v_pk_mul_f32 v[94:95], v[96:97], v[98:99]
	v_mov_b32_e32 v97, v92
	v_cndmask_b32_e64 v95, v95, -v95, s[48:49]
	v_cndmask_b32_e64 v94, v94, -v94, s[48:49]
	v_pk_fma_f32 v[2:3], v[100:101], v[2:3], v[94:95]
	v_lshlrev_b32_e32 v94, 16, v45
	v_and_b32_e32 v95, 0xffff0000, v45
	v_mov_b32_e32 v92, v91
	v_mov_b32_e32 v96, v90
	v_pk_mul_f32 v[90:91], v[92:93], v[94:95]
	v_mov_b32_e32 v93, v88
	v_cndmask_b32_e64 v91, v91, -v91, s[48:49]
	v_cndmask_b32_e64 v90, v90, -v90, s[48:49]
	v_pk_fma_f32 v[76:77], v[96:97], v[76:77], v[90:91]
	v_lshlrev_b32_e32 v90, 16, v46
	v_and_b32_e32 v91, 0xffff0000, v46
	v_mov_b32_e32 v88, v87
	v_mov_b32_e32 v92, v86
	v_pk_mul_f32 v[86:87], v[88:89], v[90:91]
	v_mov_b32_e32 v89, v84
	v_cndmask_b32_e64 v87, v87, -v87, s[48:49]
	v_cndmask_b32_e64 v86, v86, -v86, s[48:49]
	v_pk_fma_f32 v[78:79], v[92:93], v[78:79], v[86:87]
	v_lshlrev_b32_e32 v86, 16, v47
	v_and_b32_e32 v87, 0xffff0000, v47
	v_mov_b32_e32 v84, v83
	v_mov_b32_e32 v88, v82
	v_pk_mul_f32 v[82:83], v[84:85], v[86:87]
	s_nop 0
	v_cndmask_b32_e64 v83, v83, -v83, s[48:49]
	v_cndmask_b32_e64 v82, v82, -v82, s[48:49]
	v_pk_fma_f32 v[80:81], v[88:89], v[80:81], v[82:83]
.LBB0_503:
	v_cvt_pk_bf16_f32 v82, v2, v3
	v_cvt_pk_bf16_f32 v83, v76, v77
	v_cvt_pk_bf16_f32 v84, v78, v79
	s_nop 0
	v_cvt_pk_bf16_f32 v85, v80, v81
	s_waitcnt vmcnt(2)
	v_lshlrev_b32_e32 v2, 16, v48
	v_and_b32_e32 v3, 0xffff0000, v48
	v_lshlrev_b32_e32 v76, 16, v49
	v_and_b32_e32 v77, 0xffff0000, v49
	v_lshlrev_b32_e32 v80, 16, v50
	v_and_b32_e32 v81, 0xffff0000, v50
	v_lshlrev_b32_e32 v78, 16, v51
	s_andn2_b64 vcc, exec, s[38:39]
	v_and_b32_e32 v79, 0xffff0000, v51
	ds_write_b128 v160, v[82:85]
	ds_write_b128 v160, v[32:35] offset:18432
	s_cbranch_vccnz .LBB0_505
	s_waitcnt vmcnt(0)
	v_lshlrev_b32_e32 v98, 16, v52
	v_and_b32_e32 v99, 0xffff0000, v52
	v_mov_b32_e32 v82, v102
	v_mov_b32_e32 v83, v103
	v_mov_b32_e32 v84, v104
	v_mov_b32_e32 v85, v105
	v_mov_b32_e32 v86, v106
	v_mov_b32_e32 v87, v107
	v_mov_b32_e32 v88, v108
	v_mov_b32_e32 v89, v109
	v_mov_b32_e32 v90, v110
	v_mov_b32_e32 v91, v111
	v_mov_b32_e32 v92, v112
	v_mov_b32_e32 v93, v113
	v_mov_b32_e32 v94, v114
	v_mov_b32_e32 v95, v115
	v_mov_b32_e32 v96, v116
	v_mov_b32_e32 v97, v117
	v_mov_b32_e32 v101, v96
	v_mov_b32_e32 v96, v95
	v_mov_b32_e32 v100, v94
	v_pk_mul_f32 v[94:95], v[96:97], v[98:99]
	v_mov_b32_e32 v97, v92
	v_cndmask_b32_e64 v95, v95, -v95, s[48:49]
	v_cndmask_b32_e64 v94, v94, -v94, s[48:49]
	v_pk_fma_f32 v[2:3], v[100:101], v[2:3], v[94:95]
	v_lshlrev_b32_e32 v94, 16, v53
	v_and_b32_e32 v95, 0xffff0000, v53
	v_mov_b32_e32 v92, v91
	v_mov_b32_e32 v96, v90
	v_pk_mul_f32 v[90:91], v[92:93], v[94:95]
	v_mov_b32_e32 v93, v88
	v_cndmask_b32_e64 v91, v91, -v91, s[48:49]
	v_cndmask_b32_e64 v90, v90, -v90, s[48:49]
	v_pk_fma_f32 v[76:77], v[96:97], v[76:77], v[90:91]
	v_lshlrev_b32_e32 v90, 16, v54
	v_and_b32_e32 v91, 0xffff0000, v54
	v_mov_b32_e32 v88, v87
	v_mov_b32_e32 v92, v86
	v_pk_mul_f32 v[86:87], v[88:89], v[90:91]
	v_mov_b32_e32 v89, v84
	v_cndmask_b32_e64 v87, v87, -v87, s[48:49]
	v_cndmask_b32_e64 v86, v86, -v86, s[48:49]
	v_pk_fma_f32 v[80:81], v[92:93], v[80:81], v[86:87]
	v_lshlrev_b32_e32 v86, 16, v55
	v_and_b32_e32 v87, 0xffff0000, v55
	v_mov_b32_e32 v84, v83
	v_mov_b32_e32 v88, v82
	v_pk_mul_f32 v[82:83], v[84:85], v[86:87]
	s_nop 0
	v_cndmask_b32_e64 v83, v83, -v83, s[48:49]
	v_cndmask_b32_e64 v82, v82, -v82, s[48:49]
	v_pk_fma_f32 v[78:79], v[88:89], v[78:79], v[82:83]
